# phase0: cbias/weff/transposes issue all loads before waiting (de-serialized round trips)
# speedup vs baseline: 1.0109x; 1.0104x over previous
.LBB0_20:
	s_and_b64 vcc, exec, s[12:13]
	s_cbranch_vccz .LBB0_26
	s_load_dwordx16 s[36:51], s[0:1], 0x0
	s_lshl_b32 s12, s20, 2
	s_and_b32 s34, s12, 0x380
	s_add_i32 s14, s19, 0xfffff930
	s_cmp_lt_u32 s14, 8
	s_waitcnt lgkmcnt(0)
	s_cselect_b32 s17, s47, s51
	s_cselect_b32 s16, s46, s50
	s_cselect_b32 s13, s43, s45
	s_cselect_b32 s12, s42, s44
	v_lshl_add_u64 v[4:5], s[16:17], 0, v[78:79]
	v_lshl_add_u64 v[2:3], s[12:13], 0, v[76:77]
	v_lshl_add_u64 v[4:5], v[4:5], 0, s[34:35]
	v_mov_b32_e32 v6, 0
	s_mov_b32 s12, 8
	s_mov_b64 s[16:17], 0x1000
.LBB0_22:
	global_load_dwordx4 v[8:11], v[2:3], off
	global_load_dwordx4 v[12:15], v[2:3], off offset:16
	global_load_dwordx4 v[16:19], v[2:3], off offset:32
	global_load_dwordx4 v[20:23], v[2:3], off offset:48
	v_lshl_add_u64 v[40:41], v[4:5], 0, s[16:17]
	v_lshl_add_u64 v[42:43], v[40:41], 0, s[16:17]
	v_lshl_add_u64 v[44:45], v[42:43], 0, s[16:17]
	global_load_dword v24, v[4:5], off
	global_load_dword v25, v[4:5], off offset:1024
	global_load_dword v26, v[4:5], off offset:2048
	global_load_dword v27, v[4:5], off offset:3072
	global_load_dword v28, v[40:41], off
	global_load_dword v29, v[40:41], off offset:1024
	global_load_dword v30, v[40:41], off offset:2048
	global_load_dword v31, v[40:41], off offset:3072
	global_load_dword v32, v[42:43], off
	global_load_dword v33, v[42:43], off offset:1024
	global_load_dword v34, v[42:43], off offset:2048
	global_load_dword v35, v[42:43], off offset:3072
	global_load_dword v36, v[44:45], off
	global_load_dword v37, v[44:45], off offset:1024
	global_load_dword v38, v[44:45], off offset:2048
	global_load_dword v39, v[44:45], off offset:3072
	v_lshl_add_u64 v[2:3], v[2:3], 0, 64
	s_add_i32 s12, s12, -1
	s_waitcnt vmcnt(0)
	v_lshl_add_u64 v[4:5], v[44:45], 0, s[16:17]
	v_fmac_f32_e32 v6, v8, v24
	v_fmac_f32_e32 v6, v9, v25
	v_fmac_f32_e32 v6, v10, v26
	v_fmac_f32_e32 v6, v11, v27
	v_fmac_f32_e32 v6, v12, v28
	v_fmac_f32_e32 v6, v13, v29
	v_fmac_f32_e32 v6, v14, v30
	v_fmac_f32_e32 v6, v15, v31
	v_fmac_f32_e32 v6, v16, v32
	v_fmac_f32_e32 v6, v17, v33
	v_fmac_f32_e32 v6, v18, v34
	v_fmac_f32_e32 v6, v19, v35
	v_fmac_f32_e32 v6, v20, v36
	v_fmac_f32_e32 v6, v21, v37
	v_fmac_f32_e32 v6, v22, v38
	v_fmac_f32_e32 v6, v23, v39
	s_cmp_lg_u32 s12, 0
	s_cbranch_scc1 .LBB0_22
	s_barrier
	ds_write_b32 v1, v6
	s_waitcnt lgkmcnt(0)
	s_barrier
	s_and_saveexec_b64 s[12:13], s[2:3]
	s_cbranch_execz .LBB0_25
	ds_read2_b32 v[2:3], v1 offset1:32
	ds_read2_b32 v[4:5], v1 offset0:64 offset1:96
	ds_read2_b32 v[6:7], v1 offset0:128 offset1:160
	ds_read2_b32 v[8:9], v1 offset0:192 offset1:224
	v_add_u32_e32 v10, 0x400, v1
	s_waitcnt lgkmcnt(3)
	v_add_f32_e32 v2, 0, v2
	v_add_f32_e32 v2, v2, v3
	s_waitcnt lgkmcnt(2)
	v_add_f32_e32 v2, v2, v4
	v_add_f32_e32 v2, v2, v5
	s_waitcnt lgkmcnt(1)
	v_add_f32_e32 v4, v2, v6
	ds_read2_b32 v[2:3], v10 offset1:32
	v_add_f32_e32 v4, v4, v7
	s_waitcnt lgkmcnt(1)
	v_add_f32_e32 v4, v4, v8
	v_add_f32_e32 v6, v4, v9
	ds_read2_b32 v[4:5], v10 offset0:64 offset1:96
	s_waitcnt lgkmcnt(1)
	v_add_f32_e32 v2, v6, v2
	ds_read2_b32 v[6:7], v10 offset0:128 offset1:160
	v_add_f32_e32 v8, v2, v3
	ds_read2_b32 v[2:3], v10 offset0:192 offset1:224
	s_waitcnt lgkmcnt(2)
	v_add_f32_e32 v4, v8, v4
	v_add_f32_e32 v4, v4, v5
	s_waitcnt lgkmcnt(1)
	v_add_f32_e32 v4, v4, v6
	v_add_f32_e32 v4, v4, v7
	s_waitcnt lgkmcnt(0)
	v_add_f32_e32 v2, v4, v2
	v_lshl_or_b32 v66, s14, 5, v178
	v_add_f32_e32 v4, v2, v3
	v_lshl_add_u64 v[2:3], v[66:67], 2, s[74:75]
	global_store_dword v[2:3], v4, off

.LBB0_27:
	s_andn2_b64 vcc, exec, s[12:13]
	s_cbranch_vccnz .LBB0_41
	s_load_dwordx16 s[36:51], s[0:1], 0x40
	s_add_i32 s24, s19, 0xfffff970
	s_lshr_b32 s17, s24, 4
	s_lshl_b32 s16, s17, 7
	v_or_b32_e32 v2, s16, v87
	v_mov_b32_e32 v3, v67
	s_waitcnt lgkmcnt(0)
	v_lshl_add_u64 v[4:5], v[2:3], 2, s[42:43]
	s_barrier
	global_load_dword v4, v[4:5], off
	s_lshl_b32 s25, s17, 16
	v_lshl_add_u32 v5, v178, 2, s25
	s_mov_b64 s[26:27], s[40:41]
	global_load_dword v8, v5, s[26:27]
	global_load_dword v9, v5, s[26:27] offset:2048
	s_add_u32 s26, s26, 0x1000
	s_addc_u32 s27, s27, 0
	global_load_dword v10, v5, s[26:27]
	global_load_dword v11, v5, s[26:27] offset:2048
	s_add_u32 s26, s26, 0x1000
	s_addc_u32 s27, s27, 0
	global_load_dword v12, v5, s[26:27]
	global_load_dword v13, v5, s[26:27] offset:2048
	s_add_u32 s26, s26, 0x1000
	s_addc_u32 s27, s27, 0
	global_load_dword v14, v5, s[26:27]
	global_load_dword v15, v5, s[26:27] offset:2048
	s_add_u32 s26, s26, 0x1000
	s_addc_u32 s27, s27, 0
	global_load_dword v16, v5, s[26:27]
	global_load_dword v17, v5, s[26:27] offset:2048
	s_add_u32 s26, s26, 0x1000
	s_addc_u32 s27, s27, 0
	global_load_dword v18, v5, s[26:27]
	global_load_dword v19, v5, s[26:27] offset:2048
	s_add_u32 s26, s26, 0x1000
	s_addc_u32 s27, s27, 0
	global_load_dword v20, v5, s[26:27]
	global_load_dword v21, v5, s[26:27] offset:2048
	s_add_u32 s26, s26, 0x1000
	s_addc_u32 s27, s27, 0
	global_load_dword v22, v5, s[26:27]
	global_load_dword v23, v5, s[26:27] offset:2048
	s_add_u32 s26, s26, 0x1000
	s_addc_u32 s27, s27, 0
	global_load_dword v24, v5, s[26:27]
	global_load_dword v25, v5, s[26:27] offset:2048
	s_add_u32 s26, s26, 0x1000
	s_addc_u32 s27, s27, 0
	global_load_dword v26, v5, s[26:27]
	global_load_dword v27, v5, s[26:27] offset:2048
	s_add_u32 s26, s26, 0x1000
	s_addc_u32 s27, s27, 0
	global_load_dword v28, v5, s[26:27]
	global_load_dword v29, v5, s[26:27] offset:2048
	s_add_u32 s26, s26, 0x1000
	s_addc_u32 s27, s27, 0
	global_load_dword v30, v5, s[26:27]
	global_load_dword v31, v5, s[26:27] offset:2048
	s_add_u32 s26, s26, 0x1000
	s_addc_u32 s27, s27, 0
	global_load_dword v32, v5, s[26:27]
	global_load_dword v33, v5, s[26:27] offset:2048
	s_add_u32 s26, s26, 0x1000
	s_addc_u32 s27, s27, 0
	global_load_dword v34, v5, s[26:27]
	global_load_dword v35, v5, s[26:27] offset:2048
	s_add_u32 s26, s26, 0x1000
	s_addc_u32 s27, s27, 0
	global_load_dword v36, v5, s[26:27]
	global_load_dword v37, v5, s[26:27] offset:2048
	s_add_u32 s26, s26, 0x1000
	s_addc_u32 s27, s27, 0
	global_load_dword v38, v5, s[26:27]
	global_load_dword v39, v5, s[26:27] offset:2048
	s_lshl_b32 s25, s24, 6
	s_and_b32 s14, s25, 0x3c0
	v_lshl_or_b32 v3, s17, 17, v70
	v_or_b32_e32 v3, s14, v3
	s_mov_b32 s15, 0x1fc00
	v_and_or_b32 v56, v69, s15, v3
	v_lshlrev_b32_e32 v56, 2, v56
	s_mov_b64 s[26:27], s[44:45]
	global_load_dword v40, v56, s[26:27]
	s_add_u32 s26, s26, 0x8000
	s_addc_u32 s27, s27, 0
	global_load_dword v41, v56, s[26:27]
	s_add_u32 s26, s26, 0x8000
	s_addc_u32 s27, s27, 0
	global_load_dword v42, v56, s[26:27]
	s_add_u32 s26, s26, 0x8000
	s_addc_u32 s27, s27, 0
	global_load_dword v43, v56, s[26:27]
	s_add_u32 s26, s26, 0x8000
	s_addc_u32 s27, s27, 0
	global_load_dword v44, v56, s[26:27]
	s_add_u32 s26, s26, 0x8000
	s_addc_u32 s27, s27, 0
	global_load_dword v45, v56, s[26:27]
	s_add_u32 s26, s26, 0x8000
	s_addc_u32 s27, s27, 0
	global_load_dword v46, v56, s[26:27]
	s_add_u32 s26, s26, 0x8000
	s_addc_u32 s27, s27, 0
	global_load_dword v47, v56, s[26:27]
	s_add_u32 s26, s26, 0x8000
	s_addc_u32 s27, s27, 0
	global_load_dword v48, v56, s[26:27]
	s_add_u32 s26, s26, 0x8000
	s_addc_u32 s27, s27, 0
	global_load_dword v49, v56, s[26:27]
	s_add_u32 s26, s26, 0x8000
	s_addc_u32 s27, s27, 0
	global_load_dword v50, v56, s[26:27]
	s_add_u32 s26, s26, 0x8000
	s_addc_u32 s27, s27, 0
	global_load_dword v51, v56, s[26:27]
	s_add_u32 s26, s26, 0x8000
	s_addc_u32 s27, s27, 0
	global_load_dword v52, v56, s[26:27]
	s_add_u32 s26, s26, 0x8000
	s_addc_u32 s27, s27, 0
	global_load_dword v53, v56, s[26:27]
	s_add_u32 s26, s26, 0x8000
	s_addc_u32 s27, s27, 0
	global_load_dword v54, v56, s[26:27]
	s_add_u32 s26, s26, 0x8000
	s_addc_u32 s27, s27, 0
	global_load_dword v55, v56, s[26:27]
	v_lshrrev_b32_e32 v57, 7, v178
	v_mad_u32_u24 v57, v57, s18, v68
	s_waitcnt vmcnt(16)
	v_mul_f32_e32 v8, v8, v4
	v_mul_f32_e32 v9, v9, v4
	v_mul_f32_e32 v10, v10, v4
	v_mul_f32_e32 v11, v11, v4
	v_mul_f32_e32 v12, v12, v4
	v_mul_f32_e32 v13, v13, v4
	v_mul_f32_e32 v14, v14, v4
	v_mul_f32_e32 v15, v15, v4
	v_mul_f32_e32 v16, v16, v4
	v_mul_f32_e32 v17, v17, v4
	v_mul_f32_e32 v18, v18, v4
	v_mul_f32_e32 v19, v19, v4
	v_mul_f32_e32 v20, v20, v4
	v_mul_f32_e32 v21, v21, v4
	v_mul_f32_e32 v22, v22, v4
	v_mul_f32_e32 v23, v23, v4
	v_mul_f32_e32 v24, v24, v4
	v_mul_f32_e32 v25, v25, v4
	v_mul_f32_e32 v26, v26, v4
	v_mul_f32_e32 v27, v27, v4
	v_mul_f32_e32 v28, v28, v4
	v_mul_f32_e32 v29, v29, v4
	v_mul_f32_e32 v30, v30, v4
	v_mul_f32_e32 v31, v31, v4
	v_mul_f32_e32 v32, v32, v4
	v_mul_f32_e32 v33, v33, v4
	v_mul_f32_e32 v34, v34, v4
	v_mul_f32_e32 v35, v35, v4
	v_mul_f32_e32 v36, v36, v4
	v_mul_f32_e32 v37, v37, v4
	v_mul_f32_e32 v38, v38, v4
	v_mul_f32_e32 v39, v39, v4
	ds_write_b32 v57, v8
	ds_write_b32 v57, v9 offset:2064
	ds_write_b32 v57, v10 offset:4128
	ds_write_b32 v57, v11 offset:6192
	ds_write_b32 v57, v12 offset:8256
	ds_write_b32 v57, v13 offset:10320
	ds_write_b32 v57, v14 offset:12384
	ds_write_b32 v57, v15 offset:14448
	ds_write_b32 v57, v16 offset:16512
	ds_write_b32 v57, v17 offset:18576
	ds_write_b32 v57, v18 offset:20640
	ds_write_b32 v57, v19 offset:22704
	ds_write_b32 v57, v20 offset:24768
	ds_write_b32 v57, v21 offset:26832
	ds_write_b32 v57, v22 offset:28896
	ds_write_b32 v57, v23 offset:30960
	ds_write_b32 v57, v24 offset:33024
	ds_write_b32 v57, v25 offset:35088
	ds_write_b32 v57, v26 offset:37152
	ds_write_b32 v57, v27 offset:39216
	ds_write_b32 v57, v28 offset:41280
	ds_write_b32 v57, v29 offset:43344
	ds_write_b32 v57, v30 offset:45408
	ds_write_b32 v57, v31 offset:47472
	ds_write_b32 v57, v32 offset:49536
	ds_write_b32 v57, v33 offset:51600
	ds_write_b32 v57, v34 offset:53664
	ds_write_b32 v57, v35 offset:55728
	ds_write_b32 v57, v36 offset:57792
	ds_write_b32 v57, v37 offset:59856
	ds_write_b32 v57, v38 offset:61920
	ds_write_b32 v57, v39 offset:63984
	s_waitcnt vmcnt(0)
	ds_write_b32 v111, v40
	ds_write_b32 v111, v41 offset:2048
	ds_write_b32 v111, v42 offset:4096
	ds_write_b32 v111, v43 offset:6144
	ds_write_b32 v111, v44 offset:8192
	ds_write_b32 v111, v45 offset:10240
	ds_write_b32 v111, v46 offset:12288
	ds_write_b32 v111, v47 offset:14336
	ds_write_b32 v111, v48 offset:16384
	ds_write_b32 v111, v49 offset:18432
	ds_write_b32 v111, v50 offset:20480
	ds_write_b32 v111, v51 offset:22528
	ds_write_b32 v111, v52 offset:24576
	ds_write_b32 v111, v53 offset:26624
	ds_write_b32 v111, v54 offset:28672
	ds_write_b32 v111, v55 offset:30720
	v_mov_b32_e32 v4, 0
	s_movk_i32 s12, 0x8000
	v_mov_b32_e32 v3, v89
	v_mov_b32_e32 v5, v4
	v_mov_b32_e32 v18, v4
	v_mov_b32_e32 v19, v4
	v_mov_b32_e32 v16, v4
	v_mov_b32_e32 v17, v4
	v_mov_b32_e32 v14, v4
	v_mov_b32_e32 v15, v4
	v_mov_b32_e32 v12, v4
	v_mov_b32_e32 v13, v4
	v_mov_b32_e32 v10, v4
	v_mov_b32_e32 v11, v4
	v_mov_b32_e32 v8, v4
	v_mov_b32_e32 v9, v4
	v_mov_b32_e32 v6, v4
	v_mov_b32_e32 v7, v4
	s_waitcnt lgkmcnt(0)
	s_barrier

.LBB0_65:
	s_or_b64 exec, exec, s[14:15]
	v_lshrrev_b32_e32 v3, 6, v11
	v_add_u32_e32 v4, -1, v3
	v_ffbl_b32_e32 v3, v3
	v_and_b32_e32 v10, v2, v4
	v_lshrrev_b32_e32 v2, v3, v2
	v_lshlrev_b32_e32 v22, 6, v2
	v_or_b32_e32 v3, v22, v221
	v_cmp_lt_u32_e64 s[12:13], v3, v18
	v_add_u32_e32 v5, 0xfffff600, v3
	v_add_u32_e32 v14, 24, v3
	v_cndmask_b32_e64 v4, -1, v3, s[12:13]
	s_movk_i32 s12, 0xf18
	v_cmp_gt_u32_e64 s[12:13], s12, v3
	v_lshlrev_b32_e32 v24, 6, v10
	v_mov_b32_e32 v66, v67
	v_cndmask_b32_e64 v5, -1, v5, s[12:13]
	v_cmp_gt_u32_e64 s[12:13], 60, v2
	v_or_b32_e32 v16, v24, v160
	s_waitcnt lgkmcnt(0)
	v_cndmask_b32_e64 v5, v5, v14, s[12:13]
	v_cmp_gt_u32_e64 s[12:13], 20, v2
	s_barrier
	s_nop 0
	v_cndmask_b32_e64 v2, v5, v3, s[12:13]
	v_cndmask_b32_e32 v14, v4, v2, vcc
	v_cmp_lt_i32_e32 vcc, -1, v14
	v_mov_b64_e32 v[32:33], v[66:67]
	v_mov_b64_e32 v[34:35], v[66:67]
	v_mov_b64_e32 v[36:37], v[66:67]
	v_mov_b64_e32 v[38:39], v[66:67]
	v_mov_b64_e32 v[40:41], v[66:67]
	v_mov_b64_e32 v[42:43], v[66:67]
	v_mov_b64_e32 v[44:45], v[66:67]
	v_mov_b64_e32 v[46:47], v[66:67]
	s_and_saveexec_b64 s[12:13], vcc
	s_cbranch_execz .Ltp0_ld
	v_mov_b32_e32 v15, v67
	v_mad_u64_u32 v[2:3], s[14:15], v16, v18, 0
	v_lshl_add_u64 v[2:3], v[2:3], 2, v[8:9]
	v_lshl_add_u64 v[2:3], v[14:15], 2, v[2:3]
	global_load_dwordx4 v[32:35], v[2:3], off
	v_or_b32_e32 v2, v24, v224
	v_mad_u64_u32 v[2:3], s[14:15], v2, v18, 0
	v_lshl_add_u64 v[2:3], v[2:3], 2, v[8:9]
	v_lshl_add_u64 v[2:3], v[14:15], 2, v[2:3]
	global_load_dwordx4 v[36:39], v[2:3], off
	v_or_b32_e32 v2, v24, v225
	v_mad_u64_u32 v[2:3], s[14:15], v2, v18, 0
	v_lshl_add_u64 v[2:3], v[2:3], 2, v[8:9]
	v_lshl_add_u64 v[2:3], v[14:15], 2, v[2:3]
	global_load_dwordx4 v[40:43], v[2:3], off
	v_or_b32_e32 v2, v24, v226
	v_mad_u64_u32 v[2:3], s[14:15], v2, v18, 0
	v_lshl_add_u64 v[2:3], v[2:3], 2, v[8:9]
	v_lshl_add_u64 v[2:3], v[14:15], 2, v[2:3]
	global_load_dwordx4 v[44:47], v[2:3], off
.Ltp0_ld:
	s_or_b64 exec, exec, s[12:13]
	v_cmp_ne_u64_e64 s[12:13], 0, v[12:13]
	s_and_saveexec_b64 s[14:15], s[12:13]
	s_cbranch_execz .Ltp0_ns
	v_mov_b32_e32 v17, v67
	v_lshl_add_u64 v[20:21], v[16:17], 2, v[12:13]
	global_load_dword v48, v[20:21], off
	global_load_dword v49, v[20:21], off offset:64
	global_load_dword v50, v[20:21], off offset:128
	global_load_dword v51, v[20:21], off offset:192
	s_waitcnt vmcnt(0)
	v_mul_f32_e32 v32, v32, v48
	v_mul_f32_e32 v33, v33, v48
	v_mul_f32_e32 v34, v34, v48
	v_mul_f32_e32 v35, v35, v48
	v_mul_f32_e32 v36, v36, v49
	v_mul_f32_e32 v37, v37, v49
	v_mul_f32_e32 v38, v38, v49
	v_mul_f32_e32 v39, v39, v49
	v_mul_f32_e32 v40, v40, v50
	v_mul_f32_e32 v41, v41, v50
	v_mul_f32_e32 v42, v42, v50
	v_mul_f32_e32 v43, v43, v50
	v_mul_f32_e32 v44, v44, v51
	v_mul_f32_e32 v45, v45, v51
	v_mul_f32_e32 v46, v46, v51
	v_mul_f32_e32 v47, v47, v51
.Ltp0_ns:
	s_or_b64 exec, exec, s[14:15]
	v_add_u32_e32 v19, v222, v223
	v_mov_b32_e32 v66, v67
	s_waitcnt vmcnt(0)
	ds_write2_b32 v19, v32, v33 offset1:1
	ds_write2_b32 v19, v34, v35 offset0:2 offset1:3
	v_add_u32_e32 v15, 0x1040, v19
	ds_write2_b32 v15, v36, v37 offset1:1
	v_add_u32_e32 v2, 0x1048, v19
	ds_write2_b32 v2, v38, v39 offset1:1
	v_add_u32_e32 v15, 0x2080, v19
	ds_write2_b32 v15, v40, v41 offset1:1
	v_add_u32_e32 v2, 0x2088, v19
	ds_write2_b32 v2, v42, v43 offset1:1
	v_add_u32_e32 v15, 0x30c0, v19
	ds_write2_b32 v15, v44, v45 offset1:1
	v_add_u32_e32 v2, 0x30c8, v19
	ds_write2_b32 v2, v46, v47 offset1:1
	v_add_u32_e32 v2, 0x400, v229
	s_waitcnt lgkmcnt(0)
	s_barrier
	ds_read2_b32 v[4:5], v229 offset1:130
	ds_read2_b32 v[14:15], v230 offset0:65 offset1:195
	ds_read2_b32 v[8:9], v2 offset0:4 offset1:134
	v_add_u32_e32 v2, 0x400, v230
	v_add_u32_e32 v12, 0x800, v230
	ds_read2_b32 v[18:19], v2 offset0:69 offset1:199
	v_add_u32_e32 v2, 0x800, v229
	ds_read2_b32 v[16:17], v12 offset0:73 offset1:203
	v_add_u32_e32 v12, 0xc00, v229
	v_add_u32_e32 v20, 0xc00, v230
	ds_read2_b32 v[2:3], v2 offset0:8 offset1:138
	ds_read2_b32 v[12:13], v12 offset0:12 offset1:142
	ds_read2_b32 v[20:21], v20 offset0:77 offset1:207
	s_xor_b64 s[12:13], s[16:17], -1
	v_or_b32_e32 v66, v22, v227
	s_and_saveexec_b64 s[14:15], s[12:13]
	s_xor_b64 s[12:13], exec, s[14:15]
	v_mad_u64_u32 v[10:11], s[14:15], v66, v11, 0
	v_lshl_add_u64 v[6:7], v[10:11], 1, v[6:7]
	v_lshlrev_b32_e32 v66, 1, v24
	v_lshl_add_u64 v[22:23], v[6:7], 0, v[66:67]
	s_andn2_saveexec_b64 s[12:13], s[12:13]
	v_mov_b32_e32 v11, v67
	v_lshlrev_b64 v[10:11], 17, v[10:11]
	v_lshl_add_u64 v[6:7], v[6:7], 0, v[10:11]
	v_lshlrev_b64 v[10:11], 7, v[66:67]
	v_lshl_add_u64 v[22:23], v[6:7], 0, v[10:11]
	s_or_b64 exec, exec, s[12:13]
	v_lshlrev_b32_e32 v66, 1, v228
	v_lshl_add_u64 v[22:23], v[22:23], 0, v[66:67]
	s_waitcnt lgkmcnt(6)
	v_cvt_pk_bf16_f32 v4, v4, v14
	v_cvt_pk_bf16_f32 v5, v5, v15
	s_waitcnt lgkmcnt(4)
	v_cvt_pk_bf16_f32 v6, v8, v18
	v_cvt_pk_bf16_f32 v7, v9, v19
	s_waitcnt lgkmcnt(2)
	v_cvt_pk_bf16_f32 v8, v2, v16
	v_cvt_pk_bf16_f32 v9, v3, v17
	s_waitcnt lgkmcnt(0)
	v_cvt_pk_bf16_f32 v10, v12, v20
	v_cvt_pk_bf16_f32 v11, v13, v21
	global_store_dwordx4 v[22:23], v[4:7], off
	global_store_dwordx4 v[22:23], v[8:11], off offset:16

.LBB0_818:
	s_or_b64 exec, exec, s[4:5]
	v_lshrrev_b32_e32 v1, 6, v13
	v_cvt_f32_u32_e32 v2, v1
	v_sub_u32_e32 v12, 0, v1
	v_sub_u32_e32 v5, 0, v0
	v_max_i32_e32 v5, v0, v5
	v_rcp_iflag_f32_e32 v2, v2
	v_ashrrev_i32_e32 v3, 31, v0
	s_barrier
	v_mul_f32_e32 v2, 0x4f7ffffe, v2
	v_cvt_u32_f32_e32 v2, v2
	v_mul_lo_u32 v12, v12, v2
	v_mul_hi_u32 v12, v2, v12
	v_add_u32_e32 v2, v2, v12
	v_mul_hi_u32 v2, v5, v2
	v_mul_lo_u32 v12, v2, v1
	v_sub_u32_e32 v5, v5, v12
	v_add_u32_e32 v14, 1, v2
	v_cmp_ge_u32_e64 s[0:1], v5, v1
	v_sub_u32_e32 v12, v5, v1
	s_nop 0
	v_cndmask_b32_e64 v2, v2, v14, s[0:1]
	v_cndmask_b32_e64 v5, v5, v12, s[0:1]
	v_add_u32_e32 v12, 1, v2
	v_cmp_ge_u32_e64 s[0:1], v5, v1
	v_mov_b32_e32 v5, v4
	s_nop 0
	v_cndmask_b32_e64 v2, v2, v12, s[0:1]
	v_xor_b32_e32 v2, v2, v3
	v_sub_u32_e32 v2, v2, v3
	v_mul_lo_u32 v1, v2, v1
	v_lshlrev_b32_e32 v27, 6, v2
	v_sub_u32_e32 v12, v0, v1
	v_or_b32_e32 v0, v27, v221
	v_cmp_lt_i32_e64 s[0:1], v0, v20
	v_add_u32_e32 v2, 0xfffff600, v0
	v_add_u32_e32 v3, 24, v0
	v_cndmask_b32_e64 v1, -1, v0, s[0:1]
	s_movk_i32 s0, 0xf18
	v_cmp_gt_u32_e64 s[0:1], s0, v0
	v_lshlrev_b32_e32 v14, 6, v12
	v_or_b32_e32 v18, v14, v160
	v_cndmask_b32_e64 v2, -1, v2, s[0:1]
	s_movk_i32 s0, 0xf00
	v_cmp_gt_u32_e64 s[0:1], s0, v27
	v_ashrrev_i32_e32 v15, 31, v14
	s_nop 0
	v_cndmask_b32_e64 v2, v2, v3, s[0:1]
	s_movk_i32 s0, 0x500
	v_cmp_gt_i32_e64 s[0:1], s0, v0
	s_nop 1
	v_cndmask_b32_e64 v0, v2, v0, s[0:1]
	v_cndmask_b32_e32 v16, v1, v0, vcc
	v_cmp_lt_i32_e32 vcc, -1, v16
	v_mov_b64_e32 v[32:33], v[4:5]
	v_mov_b64_e32 v[34:35], v[4:5]
	v_mov_b64_e32 v[36:37], v[4:5]
	v_mov_b64_e32 v[38:39], v[4:5]
	v_mov_b64_e32 v[40:41], v[4:5]
	v_mov_b64_e32 v[42:43], v[4:5]
	v_mov_b64_e32 v[44:45], v[4:5]
	v_mov_b64_e32 v[46:47], v[4:5]
	s_and_saveexec_b64 s[0:1], vcc
	s_cbranch_execz .Ltp2_ld
	v_mov_b32_e32 v17, v4
	v_mad_u64_u32 v[0:1], s[4:5], v18, v20, 0
	v_mov_b32_e32 v2, v1
	v_mad_u64_u32 v[2:3], s[4:5], v15, v20, v[2:3]
	v_mov_b32_e32 v1, v2
	v_lshl_add_u64 v[0:1], v[0:1], 2, v[10:11]
	v_lshl_add_u64 v[0:1], v[16:17], 2, v[0:1]
	global_load_dwordx4 v[32:35], v[0:1], off
	v_or_b32_e32 v0, v14, v224
	v_mad_u64_u32 v[0:1], s[4:5], v0, v20, 0
	v_mov_b32_e32 v2, v1
	v_mad_u64_u32 v[2:3], s[4:5], v15, v20, v[2:3]
	v_mov_b32_e32 v1, v2
	v_lshl_add_u64 v[0:1], v[0:1], 2, v[10:11]
	v_lshl_add_u64 v[0:1], v[16:17], 2, v[0:1]
	global_load_dwordx4 v[36:39], v[0:1], off
	v_or_b32_e32 v0, v14, v225
	v_mad_u64_u32 v[0:1], s[4:5], v0, v20, 0
	v_mov_b32_e32 v2, v1
	v_mad_u64_u32 v[2:3], s[4:5], v15, v20, v[2:3]
	v_mov_b32_e32 v1, v2
	v_lshl_add_u64 v[0:1], v[0:1], 2, v[10:11]
	v_lshl_add_u64 v[0:1], v[16:17], 2, v[0:1]
	global_load_dwordx4 v[40:43], v[0:1], off
	v_or_b32_e32 v0, v14, v226
	v_mad_u64_u32 v[0:1], s[4:5], v0, v20, 0
	v_mov_b32_e32 v2, v1
	v_mad_u64_u32 v[2:3], s[4:5], v15, v20, v[2:3]
	v_mov_b32_e32 v1, v2
	v_lshl_add_u64 v[0:1], v[0:1], 2, v[10:11]
	v_lshl_add_u64 v[0:1], v[16:17], 2, v[0:1]
	global_load_dwordx4 v[44:47], v[0:1], off
.Ltp2_ld:
	s_or_b64 exec, exec, s[0:1]
	v_cmp_ne_u64_e64 s[0:1], 0, v[8:9]
	s_and_saveexec_b64 s[4:5], s[0:1]
	s_cbranch_execz .Ltp2_ns
	v_ashrrev_i32_e32 v19, 31, v18
	v_lshl_add_u64 v[18:19], v[18:19], 2, v[8:9]
	global_load_dword v48, v[18:19], off
	v_lshl_add_u64 v[22:23], v[14:15], 0, v[160:161]
	v_lshl_add_u64 v[22:23], v[22:23], 2, v[8:9]
	global_load_dword v49, v[22:23], off offset:64
	global_load_dword v50, v[22:23], off offset:128
	global_load_dword v51, v[22:23], off offset:192
	s_waitcnt vmcnt(0)
	v_mul_f32_e32 v32, v32, v48
	v_mul_f32_e32 v33, v33, v48
	v_mul_f32_e32 v34, v34, v48
	v_mul_f32_e32 v35, v35, v48
	v_mul_f32_e32 v36, v36, v49
	v_mul_f32_e32 v37, v37, v49
	v_mul_f32_e32 v38, v38, v49
	v_mul_f32_e32 v39, v39, v49
	v_mul_f32_e32 v40, v40, v50
	v_mul_f32_e32 v41, v41, v50
	v_mul_f32_e32 v42, v42, v50
	v_mul_f32_e32 v43, v43, v50
	v_mul_f32_e32 v44, v44, v51
	v_mul_f32_e32 v45, v45, v51
	v_mul_f32_e32 v46, v46, v51
	v_mul_f32_e32 v47, v47, v51
.Ltp2_ns:
	s_or_b64 exec, exec, s[4:5]
	v_add_u32_e32 v18, v222, v223
	v_mov_b32_e32 v5, v4
	s_waitcnt vmcnt(0)
	ds_write2_b32 v18, v32, v33 offset1:1
	ds_write2_b32 v18, v34, v35 offset0:2 offset1:3
	v_add_u32_e32 v0, 0x1040, v18
	ds_write2_b32 v0, v36, v37 offset1:1
	v_add_u32_e32 v0, 0x1048, v18
	ds_write2_b32 v0, v38, v39 offset1:1
	v_add_u32_e32 v0, 0x2080, v18
	ds_write2_b32 v0, v40, v41 offset1:1
	v_add_u32_e32 v0, 0x2088, v18
	ds_write2_b32 v0, v42, v43 offset1:1
	v_add_u32_e32 v0, 0x30c0, v18
	ds_write2_b32 v0, v44, v45 offset1:1
	v_add_u32_e32 v0, 0x30c8, v18
	ds_write2_b32 v0, v46, v47 offset1:1
	v_add_u32_e32 v0, 0x400, v229
	v_add_u32_e32 v5, 0x800, v230
	s_waitcnt lgkmcnt(0)
	s_barrier
	ds_read2_b32 v[2:3], v229 offset1:130
	ds_read2_b32 v[16:17], v230 offset0:65 offset1:195
	ds_read2_b32 v[8:9], v0 offset0:4 offset1:134
	v_add_u32_e32 v0, 0x400, v230
	ds_read2_b32 v[18:19], v5 offset0:73 offset1:203
	v_add_u32_e32 v5, 0xc00, v229
	ds_read2_b32 v[20:21], v0 offset0:69 offset1:199
	v_add_u32_e32 v0, 0x800, v229
	ds_read2_b32 v[10:11], v5 offset0:12 offset1:142
	v_add_u32_e32 v5, 0xc00, v230
	ds_read2_b32 v[0:1], v0 offset0:8 offset1:138
	ds_read2_b32 v[22:23], v5 offset0:77 offset1:207
	s_xor_b64 s[0:1], s[6:7], -1
	v_or_b32_e32 v26, v27, v227
	s_and_saveexec_b64 s[4:5], s[0:1]
	s_xor_b64 s[0:1], exec, s[4:5]
	v_mad_u64_u32 v[24:25], s[4:5], v26, v13, 0
	v_ashrrev_i32_e32 v5, 31, v27
	v_mov_b32_e32 v12, v25
	v_mad_u64_u32 v[12:13], s[4:5], v5, v13, v[12:13]
	v_mov_b32_e32 v25, v12
	v_lshl_add_u64 v[6:7], v[24:25], 1, v[6:7]
	v_lshl_add_u64 v[24:25], v[14:15], 1, v[6:7]
	s_andn2_saveexec_b64 s[0:1], s[0:1]
	s_cbranch_execz .LBB0_789
	v_ashrrev_i32_e32 v13, 31, v12
	v_ashrrev_i32_e32 v27, 31, v26
	v_lshlrev_b64 v[12:13], 17, v[12:13]
	v_lshl_add_u64 v[6:7], v[6:7], 0, v[12:13]
	v_lshlrev_b64 v[12:13], 7, v[26:27]
	v_lshl_add_u64 v[24:25], v[6:7], 0, v[12:13]
	s_branch .LBB0_789
